# hand-written layer-1 GEMM2 epilogue: permlane regroup so each f32 store writes 64 contiguous bytes per row
# speedup vs baseline: 1.5089x; 1.0007x over previous
;     __device__ __forceinline__ void operator()(const f32x4 (&acc)[2][2][4][2], const pg8::Unit& u, int, LAS unsigned char*, int wr, int wc, int fr_, int fq_) const {
;     ...
;         } else {
;             f16x8 xh[2][4][2];
; #pragma unroll
;             for (int ai = 0; ai < 2; ++ai)
; #pragma unroll
;                 for (int m = 0; m < 4; ++m)
; #pragma unroll
;                     for (int bj = 0; bj < 2; ++bj) xh[ai][m][bj] = *(const f16x8*)(XH + (size_t)(row0 + ai * 128 + m * 16) * DM + col0 + bj * 32);
; #pragma unroll
;             for (int ai = 0; ai < 2; ++ai)
; #pragma unroll
;                 for (int m = 0; m < 4; ++m) {
;                     float* dst = out + (size_t)(row0 + ai * 128 + m * 16) * DM + col0;
; #pragma unroll
;                     for (int bj = 0; bj < 2; ++bj) {
;                         f32x4 x0, x1;
; #pragma unroll
;                         for (int e = 0; e < 4; ++e) { x0[e] = (float)xh[ai][m][bj][e] + acc[ai][bj][m][0][e]; x1[e] = (float)xh[ai][m][bj][4 + e] + acc[ai][bj][m][1][e]; }
;                         *(f32x4*)(dst + bj * 32) = x0; *(f32x4*)(dst + bj * 32 + 4) = x1;
;                     }
;                 }
.LBB0_503:
	v_ashrrev_i32_e32 v187, 31, v186
	v_lshlrev_b64 v[192:193], 12, v[186:187]
	v_lshl_add_u64 v[196:197], s[38:39], 0, v[192:193]
	v_lshlrev_b32_e32 v192, 2, v188
	v_lshlrev_b32_e32 v193, 4, v234
	v_sub_u32_e32 v192, v192, v193
	v_mov_b32_e32 v193, 0
	v_lshl_add_u64 v[196:197], v[196:197], 0, v[192:193]
	s_mov_b64 s[100:101], 0x10000
	s_nop 1
	v_permlane16_swap_b32_e32 v126, v122
	v_permlane16_swap_b32_e32 v127, v123
	v_permlane16_swap_b32_e32 v128, v124
	v_permlane16_swap_b32_e32 v129, v125
	v_permlane32_swap_b32_e32 v126, v122
	v_permlane32_swap_b32_e32 v127, v123
	v_permlane32_swap_b32_e32 v128, v124
	v_permlane32_swap_b32_e32 v129, v125
	global_store_dwordx4 v[196:197], v[126:129], off
	global_store_dwordx4 v[196:197], v[122:125], off offset:64
	v_permlane16_swap_b32_e32 v118, v114
	v_permlane16_swap_b32_e32 v119, v115
	v_permlane16_swap_b32_e32 v120, v116
	v_permlane16_swap_b32_e32 v121, v117
	v_permlane32_swap_b32_e32 v118, v114
	v_permlane32_swap_b32_e32 v119, v115
	v_permlane32_swap_b32_e32 v120, v116
	v_permlane32_swap_b32_e32 v121, v117
	global_store_dwordx4 v[196:197], v[118:121], off offset:128
	global_store_dwordx4 v[196:197], v[114:117], off offset:192
	v_lshl_add_u64 v[196:197], v[196:197], 0, s[100:101]
	v_permlane16_swap_b32_e32 v110, v106
	v_permlane16_swap_b32_e32 v111, v107
	v_permlane16_swap_b32_e32 v112, v108
	v_permlane16_swap_b32_e32 v113, v109
	v_permlane32_swap_b32_e32 v110, v106
	v_permlane32_swap_b32_e32 v111, v107
	v_permlane32_swap_b32_e32 v112, v108
	v_permlane32_swap_b32_e32 v113, v109
	global_store_dwordx4 v[196:197], v[110:113], off
	global_store_dwordx4 v[196:197], v[106:109], off offset:64
	v_permlane16_swap_b32_e32 v102, v98
	v_permlane16_swap_b32_e32 v103, v99
	v_permlane16_swap_b32_e32 v104, v100
	v_permlane16_swap_b32_e32 v105, v101
	v_permlane32_swap_b32_e32 v102, v98
	v_permlane32_swap_b32_e32 v103, v99
	v_permlane32_swap_b32_e32 v104, v100
	v_permlane32_swap_b32_e32 v105, v101
	global_store_dwordx4 v[196:197], v[102:105], off offset:128
	global_store_dwordx4 v[196:197], v[98:101], off offset:192
	v_lshl_add_u64 v[196:197], v[196:197], 0, s[100:101]
	v_permlane16_swap_b32_e32 v94, v90
	v_permlane16_swap_b32_e32 v95, v91
	v_permlane16_swap_b32_e32 v96, v92
	v_permlane16_swap_b32_e32 v97, v93
	v_permlane32_swap_b32_e32 v94, v90
	v_permlane32_swap_b32_e32 v95, v91
	v_permlane32_swap_b32_e32 v96, v92
	v_permlane32_swap_b32_e32 v97, v93
	global_store_dwordx4 v[196:197], v[94:97], off
	global_store_dwordx4 v[196:197], v[90:93], off offset:64
	v_permlane16_swap_b32_e32 v86, v82
	v_permlane16_swap_b32_e32 v87, v83
	v_permlane16_swap_b32_e32 v88, v84
	v_permlane16_swap_b32_e32 v89, v85
	v_permlane32_swap_b32_e32 v86, v82
	v_permlane32_swap_b32_e32 v87, v83
	v_permlane32_swap_b32_e32 v88, v84
	v_permlane32_swap_b32_e32 v89, v85
	global_store_dwordx4 v[196:197], v[86:89], off offset:128
	global_store_dwordx4 v[196:197], v[82:85], off offset:192
	v_lshl_add_u64 v[196:197], v[196:197], 0, s[100:101]
	v_permlane16_swap_b32_e32 v78, v74
	v_permlane16_swap_b32_e32 v79, v75
	v_permlane16_swap_b32_e32 v80, v76
	v_permlane16_swap_b32_e32 v81, v77
	v_permlane32_swap_b32_e32 v78, v74
	v_permlane32_swap_b32_e32 v79, v75
	v_permlane32_swap_b32_e32 v80, v76
	v_permlane32_swap_b32_e32 v81, v77
	global_store_dwordx4 v[196:197], v[78:81], off
	global_store_dwordx4 v[196:197], v[74:77], off offset:64
	v_permlane16_swap_b32_e32 v70, v66
	v_permlane16_swap_b32_e32 v71, v67
	v_permlane16_swap_b32_e32 v72, v68
	v_permlane16_swap_b32_e32 v73, v69
	v_permlane32_swap_b32_e32 v70, v66
	v_permlane32_swap_b32_e32 v71, v67
	v_permlane32_swap_b32_e32 v72, v68
;     __device__ __forceinline__ void operator()(const f32x4 (&acc)[2][2][4][2], const pg8::Unit& u, int, LAS unsigned char*, int wr, int wc, int fr_, int fq_) const {
;     ...
;         } else {
;             f16x8 xh[2][4][2];
; #pragma unroll
;             for (int ai = 0; ai < 2; ++ai)
; #pragma unroll
;                 for (int m = 0; m < 4; ++m)
; #pragma unroll
;                     for (int bj = 0; bj < 2; ++bj) xh[ai][m][bj] = *(const f16x8*)(XH + (size_t)(row0 + ai * 128 + m * 16) * DM + col0 + bj * 32);
; #pragma unroll
;             for (int ai = 0; ai < 2; ++ai)
; #pragma unroll
;                 for (int m = 0; m < 4; ++m) {
;                     float* dst = out + (size_t)(row0 + ai * 128 + m * 16) * DM + col0;
; #pragma unroll
;                     for (int bj = 0; bj < 2; ++bj) {
;                         f32x4 x0, x1;
; #pragma unroll
;                         for (int e = 0; e < 4; ++e) { x0[e] = (float)xh[ai][m][bj][e] + acc[ai][bj][m][0][e]; x1[e] = (float)xh[ai][m][bj][4 + e] + acc[ai][bj][m][1][e]; }
;                         *(f32x4*)(dst + bj * 32) = x0; *(f32x4*)(dst + bj * 32 + 4) = x1;
;                     }
;                 }
	v_permlane32_swap_b32_e32 v73, v69
	global_store_dwordx4 v[196:197], v[70:73], off offset:128
	global_store_dwordx4 v[196:197], v[66:69], off offset:192
	s_mov_b64 s[100:101], 0x50000
	v_lshl_add_u64 v[196:197], v[196:197], 0, s[100:101]
	s_mov_b64 s[100:101], 0x10000
	v_permlane16_swap_b32_e32 v62, v58
	v_permlane16_swap_b32_e32 v63, v59
	v_permlane16_swap_b32_e32 v64, v60
	v_permlane16_swap_b32_e32 v65, v61
	v_permlane32_swap_b32_e32 v62, v58
	v_permlane32_swap_b32_e32 v63, v59
	v_permlane32_swap_b32_e32 v64, v60
	v_permlane32_swap_b32_e32 v65, v61
	global_store_dwordx4 v[196:197], v[62:65], off
	global_store_dwordx4 v[196:197], v[58:61], off offset:64
	v_permlane16_swap_b32_e32 v54, v50
	v_permlane16_swap_b32_e32 v55, v51
	v_permlane16_swap_b32_e32 v56, v52
	v_permlane16_swap_b32_e32 v57, v53
	v_permlane32_swap_b32_e32 v54, v50
	v_permlane32_swap_b32_e32 v55, v51
	v_permlane32_swap_b32_e32 v56, v52
	v_permlane32_swap_b32_e32 v57, v53
	global_store_dwordx4 v[196:197], v[54:57], off offset:128
	global_store_dwordx4 v[196:197], v[50:53], off offset:192
	v_lshl_add_u64 v[196:197], v[196:197], 0, s[100:101]
	v_permlane16_swap_b32_e32 v46, v42
	v_permlane16_swap_b32_e32 v47, v43
	v_permlane16_swap_b32_e32 v48, v44
	v_permlane16_swap_b32_e32 v49, v45
	v_permlane32_swap_b32_e32 v46, v42
	v_permlane32_swap_b32_e32 v47, v43
	v_permlane32_swap_b32_e32 v48, v44
	v_permlane32_swap_b32_e32 v49, v45
	global_store_dwordx4 v[196:197], v[46:49], off
	global_store_dwordx4 v[196:197], v[42:45], off offset:64
	v_permlane16_swap_b32_e32 v38, v34
	v_permlane16_swap_b32_e32 v39, v35
	v_permlane16_swap_b32_e32 v40, v36
	v_permlane16_swap_b32_e32 v41, v37
	v_permlane32_swap_b32_e32 v38, v34
	v_permlane32_swap_b32_e32 v39, v35
	v_permlane32_swap_b32_e32 v40, v36
	v_permlane32_swap_b32_e32 v41, v37
	global_store_dwordx4 v[196:197], v[38:41], off offset:128
	global_store_dwordx4 v[196:197], v[34:37], off offset:192
	v_lshl_add_u64 v[196:197], v[196:197], 0, s[100:101]
	v_permlane16_swap_b32_e32 v30, v26
	v_permlane16_swap_b32_e32 v31, v27
	v_permlane16_swap_b32_e32 v32, v28
	v_permlane16_swap_b32_e32 v33, v29
	v_permlane32_swap_b32_e32 v30, v26
	v_permlane32_swap_b32_e32 v31, v27
	v_permlane32_swap_b32_e32 v32, v28
	v_permlane32_swap_b32_e32 v33, v29
	global_store_dwordx4 v[196:197], v[30:33], off
	global_store_dwordx4 v[196:197], v[26:29], off offset:64
	v_permlane16_swap_b32_e32 v22, v18
	v_permlane16_swap_b32_e32 v23, v19
	v_permlane16_swap_b32_e32 v24, v20
	v_permlane16_swap_b32_e32 v25, v21
	v_permlane32_swap_b32_e32 v22, v18
	v_permlane32_swap_b32_e32 v23, v19
	v_permlane32_swap_b32_e32 v24, v20
	v_permlane32_swap_b32_e32 v25, v21
	global_store_dwordx4 v[196:197], v[22:25], off offset:128
	global_store_dwordx4 v[196:197], v[18:21], off offset:192
	v_lshl_add_u64 v[196:197], v[196:197], 0, s[100:101]
	v_permlane16_swap_b32_e32 v14, v10
	v_permlane16_swap_b32_e32 v15, v11
	v_permlane16_swap_b32_e32 v16, v12
	v_permlane16_swap_b32_e32 v17, v13
	v_permlane32_swap_b32_e32 v14, v10
	v_permlane32_swap_b32_e32 v15, v11
	v_permlane32_swap_b32_e32 v16, v12
	v_permlane32_swap_b32_e32 v17, v13
	global_store_dwordx4 v[196:197], v[14:17], off
	global_store_dwordx4 v[196:197], v[10:13], off offset:64
	v_permlane16_swap_b32_e32 v6, v2
	v_permlane16_swap_b32_e32 v7, v3
	v_permlane16_swap_b32_e32 v8, v4
	v_permlane16_swap_b32_e32 v9, v5
	v_permlane32_swap_b32_e32 v6, v2
	v_permlane32_swap_b32_e32 v7, v3
	v_permlane32_swap_b32_e32 v8, v4
	v_permlane32_swap_b32_e32 v9, v5
	global_store_dwordx4 v[196:197], v[6:9], off offset:128
	global_store_dwordx4 v[196:197], v[2:5], off offset:192
	s_branch .LBB0_502
